# LRU final-scan: 16 ds_read_u16 of the y tile hoisted ahead of the serial scan (one LDS wait instead of 16)
# speedup vs baseline: 1.0019x; 1.0019x over previous
; __device__ __forceinline__ unsigned pk_bf16(float lo, float hi) { typedef __bf16 b2_t __attribute__((ext_vector_type(2))); f32x2 v = {lo, hi}; b2_t b = __builtin_convertvector(v, b2_t); return __builtin_bit_cast(unsigned, b); }
; #define LAS __attribute__((address_space(3)))
; #define LDS_BARRIER() do { asm volatile("s_waitcnt lgkmcnt(0)" ::: "memory"); __builtin_amdgcn_s_barrier(); asm volatile("" ::: "memory"); } while (0)
; __device__ __forceinline__ void lru_phase(LAS unsigned char* lds, const bf16* XB, const bf16* Y, bf16* HY, const bf16* WRt, const bf16* WIt,
;         const float* convw, const float* convb, const float* br, const float* bi, const float* lam, unsigned long long* gran, int G, int bid, int wave_s) {
;     ...
;         {
;             float h = 0.f;
;             for (int kk = 0; kk < ch; ++kk) h = pA[kk * 64 + d] * h + pH[kk * 64 + d];
;             for (int s = 0; s < 7; ++s) { if (s < sg) h = segA[s * 64 + d] * h + segH[s * 64 + d]; }
; #pragma unroll
;             for (int i = 0; i < 16; ++i) { const int t = tb + i; h = av[i] * h + uv[i];
;                 const float yv_ = __uint_as_float((unsigned)yL[t * KP + d] << 16);
;                 xcB[t * KP + d] = (bf16)(pk_bf16(h * yv_, 0.f) & 0xffffu); }
;         }
;         LDS_BARRIER();
; #pragma unroll
;         for (int r = 0; r < 2; ++r) *(v4u*)(HY + (size_t)(b * SEQ + t0 + st + 64 * r) * D + c0 + cc) = *(const LAS v4u*)(xcB + (st + 64 * r) * KP + cc);
.LBB0_2103:
	s_or_b64 exec, exec, s[60:61]
	ds_read_u16 v235, v154
	ds_read_u16 v236, v156
	ds_read_u16 v237, v158
	ds_read_u16 v238, v160
	ds_read_u16 v239, v162
	ds_read_u16 v240, v164
	ds_read_u16 v241, v166
	ds_read_u16 v242, v168
	ds_read_u16 v243, v170
	ds_read_u16 v244, v172
	ds_read_u16 v245, v175
	ds_read_u16 v246, v177
	ds_read_u16 v247, v179
	ds_read_u16 v248, v181
	ds_read_u16 v249, v183
	ds_read_u16 v250, v185
	v_fmac_f32_e32 v209, v207, v1
	v_fmac_f32_e32 v211, v208, v209
	v_fmac_f32_e32 v213, v210, v211
	v_fmac_f32_e32 v215, v212, v213
	v_fmac_f32_e32 v217, v214, v215
	v_fmac_f32_e32 v219, v216, v217
	v_fmac_f32_e32 v221, v218, v219
	v_fmac_f32_e32 v227, v220, v221
	v_fmac_f32_e32 v231, v225, v227
	v_fmac_f32_e32 v234, v230, v231
	v_fmac_f32_e32 v226, v233, v234
	v_fmac_f32_e32 v223, v224, v226
	v_fmac_f32_e32 v229, v222, v223
	v_fmac_f32_e32 v232, v228, v229
	v_fmac_f32_e32 v98, v30, v232
	s_and_b32 s60, s84, 0xffffff80
	s_lshl_b32 s61, s82, 11
	s_add_i32 s61, s61, s60
	s_lshl_b32 s6, s91, 1
	s_mov_b32 s7, s42
	v_fmac_f32_e32 v99, v31, v98
	s_mov_b32 s84, s93
	v_lshl_add_u64 v[0:1], v[80:81], 0, s[6:7]
	v_add_u32_e32 v2, s61, v100
	v_ashrrev_i32_e32 v3, 31, v2
	v_lshlrev_b64 v[2:3], 11, v[2:3]
	v_lshl_add_u64 v[8:9], v[0:1], 0, v[2:3]
	v_add_co_u32_e32 v10, vcc, 0x20000, v8
	s_waitcnt lgkmcnt(0)
	v_lshlrev_b32_e32 v251, 16, v235
	v_mul_f32_e32 v251, v209, v251
	v_cvt_pk_bf16_f32 v251, v251, s0
	ds_write_b16 v155, v251
	v_lshlrev_b32_e32 v251, 16, v236
	v_mul_f32_e32 v251, v211, v251
	v_cvt_pk_bf16_f32 v251, v251, s0
	ds_write_b16 v157, v251
	v_lshlrev_b32_e32 v251, 16, v237
	v_mul_f32_e32 v251, v213, v251
	v_cvt_pk_bf16_f32 v251, v251, s0
	ds_write_b16 v159, v251
	v_lshlrev_b32_e32 v251, 16, v238
	v_mul_f32_e32 v251, v215, v251
	v_cvt_pk_bf16_f32 v251, v251, s0
	ds_write_b16 v161, v251
	v_lshlrev_b32_e32 v251, 16, v239
	v_mul_f32_e32 v251, v217, v251
	v_cvt_pk_bf16_f32 v251, v251, s0
	ds_write_b16 v163, v251
	v_lshlrev_b32_e32 v251, 16, v240
	v_mul_f32_e32 v251, v219, v251
	v_cvt_pk_bf16_f32 v251, v251, s0
	ds_write_b16 v165, v251
	v_lshlrev_b32_e32 v251, 16, v241
	v_mul_f32_e32 v251, v221, v251
	v_cvt_pk_bf16_f32 v251, v251, s0
	ds_write_b16 v167, v251
	v_lshlrev_b32_e32 v251, 16, v242
	v_mul_f32_e32 v251, v227, v251
	v_cvt_pk_bf16_f32 v251, v251, s0
	ds_write_b16 v169, v251
	v_lshlrev_b32_e32 v251, 16, v243
	v_mul_f32_e32 v251, v231, v251
	v_cvt_pk_bf16_f32 v251, v251, s0
	ds_write_b16 v171, v251
	v_lshlrev_b32_e32 v251, 16, v244
	v_mul_f32_e32 v251, v234, v251
	v_cvt_pk_bf16_f32 v251, v251, s0
	ds_write_b16 v173, v251
	v_lshlrev_b32_e32 v251, 16, v245
	v_mul_f32_e32 v251, v226, v251
	v_cvt_pk_bf16_f32 v251, v251, s0
	ds_write_b16 v176, v251
	v_lshlrev_b32_e32 v251, 16, v246
	v_mul_f32_e32 v251, v223, v251
	v_cvt_pk_bf16_f32 v251, v251, s0
	ds_write_b16 v178, v251
	v_lshlrev_b32_e32 v251, 16, v247
	v_mul_f32_e32 v251, v229, v251
	v_cvt_pk_bf16_f32 v251, v251, s0
	ds_write_b16 v180, v251
	v_lshlrev_b32_e32 v251, 16, v248
	v_mul_f32_e32 v251, v232, v251
	v_cvt_pk_bf16_f32 v251, v251, s0
	ds_write_b16 v182, v251
	v_lshlrev_b32_e32 v251, 16, v249
	v_mul_f32_e32 v251, v98, v251
	v_cvt_pk_bf16_f32 v251, v251, s0
	ds_write_b16 v184, v251
	v_lshlrev_b32_e32 v251, 16, v250
	v_mul_f32_e32 v251, v99, v251
	v_cvt_pk_bf16_f32 v251, v251, s0
	ds_write_b16 v186, v251
	s_waitcnt lgkmcnt(0)
	s_barrier
	ds_read_b128 v[0:3], v206
	ds_read_b128 v[4:7], v117
	v_addc_co_u32_e32 v11, vcc, 0, v9, vcc
	s_andn2_b64 vcc, exec, s[58:59]
	s_waitcnt lgkmcnt(1)
	global_store_dwordx4 v[8:9], v[0:3], off sc1
	s_waitcnt lgkmcnt(0)
	global_store_dwordx4 v[10:11], v[4:7], off sc1
	s_cbranch_vccz .LBB0_2229
